# grid barrier leader path: release the XCD generation word first, then invalidate own L1 (reordered, same instructions)
# baseline (speedup 1.0000x reference)
.LBB0_171:
	s_or_b64 exec, exec, s[4:5]
	s_mov_b64 s[4:5], exec
	v_mbcnt_lo_u32_b32 v2, s4, 0
	v_mbcnt_hi_u32_b32 v2, s5, v2
	v_cmp_eq_u32_e32 vcc, 0, v2
	s_and_saveexec_b64 s[6:7], vcc
	s_cbranch_execz .LBB0_173
	s_bcnt1_i32_b64 s4, s[4:5]
	v_mov_b32_e32 v2, 0x2000
	v_mov_b32_e32 v3, s4
	global_atomic_add v2, v3, s[2:3] offset:1024
.LBB0_173:
	s_or_b64 exec, exec, s[6:7]
	buffer_inv sc1
	s_waitcnt vmcnt(0)

.LBB0_187:
	s_or_b64 exec, exec, s[28:29]
	buffer_inv sc1
	s_waitcnt vmcnt(0)

.LBB0_263:
	s_or_b64 exec, exec, s[26:27]
	s_mov_b64 s[26:27], exec
	v_mbcnt_lo_u32_b32 v0, s26, 0
	v_mbcnt_hi_u32_b32 v0, s27, v0
	v_cmp_eq_u32_e32 vcc, 0, v0
	s_and_saveexec_b64 s[28:29], vcc
	s_cbranch_execz .LBB0_265
	s_bcnt1_i32_b64 s2, s[26:27]
	v_mov_b32_e32 v0, s2
	v_readlane_b32 s2, v253, 52
	v_readlane_b32 s3, v253, 53
	s_nop 4
	global_atomic_add v199, v0, s[2:3]

.LBB0_822:
	s_or_b64 exec, exec, s[26:27]
	s_mov_b64 s[26:27], exec
	v_mbcnt_lo_u32_b32 v0, s26, 0
	v_mbcnt_hi_u32_b32 v0, s27, v0
	v_cmp_eq_u32_e32 vcc, 0, v0
	s_and_saveexec_b64 s[28:29], vcc
	s_cbranch_execz .LBB0_187
	s_bcnt1_i32_b64 s2, s[26:27]
	v_mov_b32_e32 v0, s2
	v_readlane_b32 s2, v253, 52
	v_readlane_b32 s3, v253, 53
	s_nop 4
	global_atomic_add v199, v0, s[2:3]
	s_branch .LBB0_187
